# v14 plus retention units no longer drain the second tile's LDS-DMA before the key loop (counted wait at the loop top covers Q and tile 0)
# baseline (speedup 1.0000x reference)
.LBB0_230:
	s_min_u32 s2, s5, 0x100
	s_lshl_b32 s2, s2, 8
	s_and_b32 s33, s2, 0x300
	s_add_i32 s40, s58, s33
	s_ashr_i32 s41, s40, 31
	s_lshl_b64 s[54:55], s[40:41], 9
	v_readlane_b32 s1, v254, 52
	s_add_u32 s36, s1, s54
	v_readlane_b32 s1, v254, 53
	s_addc_u32 s41, s1, s55
	s_lshl_b32 s2, s0, 6
	s_lshl_b32 s60, s0, 7
	s_waitcnt vmcnt(0)
	v_mul_f32_e32 v0, 0xbfb8aa3b, v3
	s_add_u32 s66, s36, s60
	v_exp_f32_e32 v3, v0
	s_addc_u32 s67, s41, 0
	s_lshl_b64 s[58:59], s[58:59], 9
	v_readlane_b32 s0, v254, 54
	s_add_u32 s0, s0, s58
	v_readlane_b32 s1, v254, 56
	s_addc_u32 s36, s1, s59
	s_add_u32 s62, s0, s60
	v_add_f32_e32 v4, 1.0, v3
	s_addc_u32 s63, s36, 0
	v_readlane_b32 s0, v254, 57
	v_add_f32_e32 v0, -1.0, v4
	s_add_u32 s0, s0, s58
	v_readlane_b32 s1, v254, 58
	v_sub_f32_e32 v1, v0, v4
	s_addc_u32 s36, s1, s59
	v_add_f32_e32 v1, 1.0, v1
	v_sub_f32_e32 v0, v3, v0
	s_add_u32 s64, s0, s60
	v_add_f32_e32 v5, v0, v1
	v_frexp_mant_f32_e32 v6, v4
	v_cvt_f64_f32_e32 v[0:1], v4
	s_mov_b32 s0, 0x3f2aaaab
	v_frexp_exp_i32_f64_e32 v0, v[0:1]
	v_cmp_gt_f32_e32 vcc, s0, v6
	s_mov_b32 s1, 0x3f317218
	s_addc_u32 s65, s36, 0
	v_subbrev_co_u32_e32 v0, vcc, 0, v0, vcc
	v_sub_u32_e32 v1, 0, v0
	v_ldexp_f32 v4, v4, v1
	v_ldexp_f32 v1, v5, v1
	v_add_f32_e32 v5, -1.0, v4
	v_add_f32_e32 v8, 1.0, v4
	v_add_f32_e32 v6, 1.0, v5
	v_add_f32_e32 v9, -1.0, v8
	v_sub_f32_e32 v6, v4, v6
	v_sub_f32_e32 v4, v4, v9
	v_add_f32_e32 v6, v1, v6
	v_add_f32_e32 v1, v1, v4
	v_add_f32_e32 v4, v8, v1
	v_rcp_f32_e32 v9, v4
	v_add_f32_e32 v7, v5, v6
	v_sub_f32_e32 v5, v7, v5
	v_sub_f32_e32 v5, v6, v5
	v_sub_f32_e32 v6, v4, v8
	v_sub_f32_e32 v1, v1, v6
	v_mul_f32_e32 v6, v7, v9
	v_mul_f32_e32 v8, v4, v6
	v_fma_f32 v10, v6, v4, -v8
	v_fmac_f32_e32 v10, v6, v1
	v_add_f32_e32 v11, v8, v10
	v_sub_f32_e32 v12, v7, v11
	v_sub_f32_e32 v7, v7, v12
	v_sub_f32_e32 v8, v11, v8
	v_sub_f32_e32 v7, v7, v11
	v_add_f32_e32 v5, v5, v7
	v_sub_f32_e32 v7, v8, v10
	v_add_f32_e32 v5, v7, v5
	v_add_f32_e32 v7, v12, v5
	v_mul_f32_e32 v8, v9, v7
	v_mul_f32_e32 v10, v4, v8
	v_fma_f32 v4, v8, v4, -v10
	v_fmac_f32_e32 v4, v8, v1
	v_sub_f32_e32 v1, v12, v7
	v_add_f32_e32 v1, v5, v1
	v_add_f32_e32 v5, v10, v4
	v_sub_f32_e32 v11, v7, v5
	v_sub_f32_e32 v7, v7, v11
	v_sub_f32_e32 v10, v5, v10
	v_sub_f32_e32 v5, v7, v5
	v_add_f32_e32 v1, v1, v5
	v_sub_f32_e32 v4, v10, v4
	v_cvt_f32_i32_e32 v0, v0
	v_add_f32_e32 v1, v4, v1
	v_add_f32_e32 v4, v6, v8
	v_add_f32_e32 v1, v11, v1
	v_sub_f32_e32 v5, v4, v6
	v_mul_f32_e32 v1, v9, v1
	v_sub_f32_e32 v5, v8, v5
	v_add_f32_e32 v1, v5, v1
	v_mul_f32_e32 v8, 0x3f317218, v0
	v_add_f32_e32 v5, v4, v1
	v_fma_f32 v9, v0, s1, -v8
	v_mul_f32_e32 v6, v5, v5
	v_mov_b32_e32 v12, 0x3ecc95a3
	v_fmac_f32_e32 v9, 0xb102e308, v0
	v_sub_f32_e32 v0, v5, v4
	v_fmamk_f32 v7, v6, 0x3e9b6dac, v12
	v_sub_f32_e32 v0, v1, v0
	v_add_f32_e32 v1, v8, v9
	v_fmaak_f32 v7, v6, v7, 0x3f2aaada
	v_sub_f32_e32 v4, v1, v8
	v_ldexp_f32 v8, v5, 1
	v_mul_f32_e32 v5, v5, v6
	v_mul_f32_e32 v5, v5, v7
	v_add_f32_e32 v6, v8, v5
	v_sub_f32_e32 v7, v6, v8
	v_ldexp_f32 v0, v0, 1
	v_sub_f32_e32 v5, v5, v7
	v_add_f32_e32 v0, v0, v5
	v_add_f32_e32 v5, v6, v0
	v_sub_f32_e32 v6, v5, v6
	v_sub_f32_e32 v0, v0, v6
	v_add_f32_e32 v6, v1, v5
	v_sub_f32_e32 v7, v6, v1
	v_sub_f32_e32 v8, v6, v7
	v_sub_f32_e32 v4, v9, v4
	v_sub_f32_e32 v1, v1, v8
	v_sub_f32_e32 v5, v5, v7
	v_add_f32_e32 v1, v5, v1
	v_add_f32_e32 v5, v4, v0
	v_sub_f32_e32 v7, v5, v4
	v_sub_f32_e32 v8, v5, v7
	v_sub_f32_e32 v4, v4, v8
	v_sub_f32_e32 v0, v0, v7
	v_add_f32_e32 v1, v5, v1
	v_add_f32_e32 v0, v0, v4
	v_add_f32_e32 v4, v6, v1
	v_sub_f32_e32 v5, v4, v6
	v_sub_f32_e32 v1, v1, v5
	v_add_f32_e32 v0, v0, v1
	s_mov_b32 s36, 0x7f800000
	v_mul_f32_e32 v1, 0xbfb8aa3b, v2
	v_add_f32_e32 v0, v4, v0
	v_cmp_neq_f32_e32 vcc, s36, v3
	v_mov_b32_e32 v13, 0x7f800000
	v_exp_f32_e32 v2, v1
	v_cndmask_b32_e32 v0, v13, v0, vcc
	v_cmp_ngt_f32_e32 vcc, -1.0, v3
	v_mov_b32_e32 v14, 0x7fc00000
	v_mov_b32_e32 v15, 0xff800000
	v_cndmask_b32_e32 v0, v14, v0, vcc
	v_cmp_neq_f32_e32 vcc, -1.0, v3
	s_mov_b32 s50, 0x33800000
	v_mov_b32_e32 v80, v188
	v_cndmask_b32_e32 v0, v15, v0, vcc
	v_cmp_lt_f32_e64 vcc, |v3|, s50
	s_waitcnt lgkmcnt(0)
	s_barrier
	v_cndmask_b32_e32 v0, v0, v3, vcc
	v_add_f32_e32 v3, 1.0, v2
	v_mul_f32_e32 v115, 0xbfb8aa3b, v0
	v_add_f32_e32 v0, -1.0, v3
	v_sub_f32_e32 v1, v0, v3
	v_add_f32_e32 v1, 1.0, v1
	v_sub_f32_e32 v0, v2, v0
	v_add_f32_e32 v4, v0, v1
	v_frexp_mant_f32_e32 v5, v3
	v_cvt_f64_f32_e32 v[0:1], v3
	v_frexp_exp_i32_f64_e32 v0, v[0:1]
	v_cmp_gt_f32_e32 vcc, s0, v5
	s_mov_b64 s[54:55], 0x8000
	s_nop 0
	v_subbrev_co_u32_e32 v0, vcc, 0, v0, vcc
	v_sub_u32_e32 v1, 0, v0
	v_ldexp_f32 v3, v3, v1
	v_ldexp_f32 v1, v4, v1
	v_add_f32_e32 v4, -1.0, v3
	v_add_f32_e32 v7, 1.0, v3
	v_add_f32_e32 v5, 1.0, v4
	v_add_f32_e32 v8, -1.0, v7
	v_sub_f32_e32 v5, v3, v5
	v_sub_f32_e32 v3, v3, v8
	v_add_f32_e32 v5, v1, v5
	v_add_f32_e32 v1, v1, v3
	v_add_f32_e32 v3, v7, v1
	v_rcp_f32_e32 v8, v3
	v_add_f32_e32 v6, v4, v5
	v_sub_f32_e32 v4, v6, v4
	v_sub_f32_e32 v4, v5, v4
	v_sub_f32_e32 v5, v3, v7
	v_sub_f32_e32 v1, v1, v5
	v_mul_f32_e32 v5, v6, v8
	v_mul_f32_e32 v7, v3, v5
	v_fma_f32 v9, v5, v3, -v7
	v_fmac_f32_e32 v9, v5, v1
	v_add_f32_e32 v10, v7, v9
	v_sub_f32_e32 v11, v6, v10
	v_sub_f32_e32 v6, v6, v11
	v_sub_f32_e32 v7, v10, v7
	v_sub_f32_e32 v6, v6, v10
	v_add_f32_e32 v4, v4, v6
	v_sub_f32_e32 v6, v7, v9
	v_add_f32_e32 v4, v6, v4
	v_add_f32_e32 v6, v11, v4
	v_mul_f32_e32 v7, v8, v6
	v_mul_f32_e32 v9, v3, v7
	v_fma_f32 v3, v7, v3, -v9
	v_fmac_f32_e32 v3, v7, v1
	v_sub_f32_e32 v1, v11, v6
	v_add_f32_e32 v1, v4, v1
	v_add_f32_e32 v4, v9, v3
	v_sub_f32_e32 v10, v6, v4
	v_sub_f32_e32 v6, v6, v10
	v_sub_f32_e32 v9, v4, v9
	v_sub_f32_e32 v4, v6, v4
	v_add_f32_e32 v1, v1, v4
	v_sub_f32_e32 v3, v9, v3
	v_cvt_f32_i32_e32 v0, v0
	v_add_f32_e32 v1, v3, v1
	v_add_f32_e32 v3, v5, v7
	v_add_f32_e32 v1, v10, v1
	v_sub_f32_e32 v4, v3, v5
	v_mul_f32_e32 v1, v8, v1
	v_sub_f32_e32 v4, v7, v4
	v_add_f32_e32 v1, v4, v1
	v_mul_f32_e32 v7, 0x3f317218, v0
	v_add_f32_e32 v4, v3, v1
	v_fma_f32 v8, v0, s1, -v7
	v_mul_f32_e32 v5, v4, v4
	v_fmac_f32_e32 v8, 0xb102e308, v0
	v_sub_f32_e32 v0, v4, v3
	v_fmamk_f32 v6, v5, 0x3e9b6dac, v12
	v_sub_f32_e32 v0, v1, v0
	v_add_f32_e32 v1, v7, v8
	v_fmaak_f32 v6, v5, v6, 0x3f2aaada
	v_sub_f32_e32 v3, v1, v7
	v_ldexp_f32 v7, v4, 1
	v_mul_f32_e32 v4, v4, v5
	v_mul_f32_e32 v4, v4, v6
	v_add_f32_e32 v5, v7, v4
	v_sub_f32_e32 v6, v5, v7
	v_ldexp_f32 v0, v0, 1
	v_sub_f32_e32 v4, v4, v6
	v_add_f32_e32 v0, v0, v4
	v_add_f32_e32 v4, v5, v0
	v_sub_f32_e32 v5, v4, v5
	v_sub_f32_e32 v0, v0, v5
	v_add_f32_e32 v5, v1, v4
	v_sub_f32_e32 v6, v5, v1
	v_sub_f32_e32 v7, v5, v6
	v_sub_f32_e32 v3, v8, v3
	v_sub_f32_e32 v1, v1, v7
	v_sub_f32_e32 v4, v4, v6
	v_add_f32_e32 v1, v4, v1
	v_add_f32_e32 v4, v3, v0
	v_sub_f32_e32 v6, v4, v3
	v_sub_f32_e32 v7, v4, v6
	v_sub_f32_e32 v3, v3, v7
	v_sub_f32_e32 v0, v0, v6
	v_add_f32_e32 v1, v4, v1
	v_add_f32_e32 v0, v0, v3
	v_add_f32_e32 v3, v5, v1
	v_sub_f32_e32 v4, v3, v5
	v_sub_f32_e32 v1, v1, v4
	v_add_f32_e32 v0, v0, v1
	v_add_f32_e32 v0, v3, v0
	v_cmp_neq_f32_e32 vcc, s36, v2
	v_ashrrev_i32_e32 v4, 3, v80
	v_add_u32_e32 v5, s10, v4
	v_cndmask_b32_e32 v0, v13, v0, vcc
	v_cmp_ngt_f32_e32 vcc, -1.0, v2
	v_and_b32_e32 v114, 31, v80
	v_or_b32_e32 v116, s51, v114
	v_cndmask_b32_e32 v0, v14, v0, vcc
	v_cmp_neq_f32_e32 vcc, -1.0, v2
	v_ashrrev_i32_e32 v136, 5, v80
	v_ashrrev_i32_e32 v117, 31, v116
	v_cndmask_b32_e32 v0, v15, v0, vcc
	v_cmp_lt_f32_e64 vcc, |v2|, s50
	v_readlane_b32 s1, v253, 62
	v_lshlrev_b32_e32 v141, 2, v136
	v_cndmask_b32_e32 v0, v0, v2, vcc
	v_mul_f32_e32 v137, 0xbfb8aa3b, v0
	v_lshrrev_b32_e32 v0, 1, v5
	v_xor_b32_e32 v0, v0, v80
	v_lshlrev_b32_e32 v0, 3, v0
	v_and_b32_e32 v6, 56, v0
	v_lshlrev_b32_e32 v0, 3, v80
	v_and_b32_e32 v142, 24, v0
	v_lshlrev_b64 v[0:1], 9, v[116:117]
	v_lshlrev_b32_e32 v2, 3, v136
	v_lshl_add_u64 v[0:1], s[66:67], 0, v[0:1]
	v_ashrrev_i32_e32 v3, 31, v2
	v_lshl_add_u64 v[0:1], v[2:3], 1, v[0:1]
	global_load_dwordx4 v[94:97], v[0:1], off
	global_load_dwordx4 v[90:93], v[0:1], off offset:32
	global_load_dwordx4 v[86:89], v[0:1], off offset:64
	global_load_dwordx4 v[82:85], v[0:1], off offset:96
	v_lshlrev_b32_e32 v1, 6, v80
	v_readlane_b32 s66, v255, 13
	v_lshl_or_b32 v0, v5, 8, v6
	v_and_b32_e32 v5, 0xffffff00, v1
	v_or_b32_e32 v1, s66, v142
	v_add_u32_e32 v2, v1, v5
	v_ashrrev_i32_e32 v1, 31, v0
	v_lshl_add_u64 v[0:1], v[0:1], 1, s[62:63]
	s_mov_b32 s0, m0
	s_mov_b32 m0, s17
	s_nop 0
	global_load_lds_dwordx4 v[0:1], off
	s_mov_b32 m0, s0
	v_ashrrev_i32_e32 v3, 31, v2
	v_lshl_add_u64 v[2:3], v[2:3], 1, s[64:65]
	s_mov_b32 s0, m0
	s_mov_b32 m0, s38
	s_nop 0
	global_load_lds_dwordx4 v[2:3], off
	s_mov_b32 m0, s0
	v_lshl_add_u64 v[0:1], v[0:1], 0, s[54:55]
	s_add_i32 s0, s16, s1
	s_mov_b32 s36, m0
	s_mov_b32 m0, s0
	s_nop 0
	global_load_lds_dwordx4 v[0:1], off
	s_mov_b32 m0, s36
	v_sub_u32_e32 v0, 63, v80
	v_cvt_f32_i32_e32 v7, v0
	v_lshl_add_u64 v[0:1], v[2:3], 0, s[54:55]
	s_add_i32 s0, s80, s1
	s_mov_b32 s36, m0
	s_mov_b32 m0, s0
	s_nop 0
	global_load_lds_dwordx4 v[0:1], off
	s_mov_b32 m0, s36
	v_cvt_f32_i32_e32 v1, v80
	v_mul_f32_e32 v0, v115, v7
	v_exp_f32_e32 v0, v0
	v_cvt_f32_i32_e32 v3, v116
	v_mul_f32_e32 v1, v137, v1
	v_exp_f32_e32 v1, v1
	v_sub_u32_e32 v7, 0xff, v116
	v_cvt_f32_i32_e32 v7, v7
	v_readlane_b32 s0, v255, 12
	s_or_b32 s50, s33, 0xff
	s_sub_i32 s36, s33, 63
	v_lshl_add_u32 v2, v80, 2, s0
	ds_write2st64_b32 v2, v0, v1 offset1:1
	v_mul_f32_e32 v0, v115, v3
	v_exp_f32_e32 v139, v0
	v_mul_f32_e32 v0, v137, v7
	v_exp_f32_e32 v138, v0
	v_lshrrev_b32_e32 v0, 2, v80
	v_and_or_b32 v0, v0, 3, v141
	v_lshlrev_b32_e32 v117, 6, v0
	v_lshlrev_b32_e32 v0, 1, v80
	v_and_b32_e32 v143, 32, v0
	v_lshrrev_b32_e32 v0, 1, v80
	v_bitop3_b32 v1, v0, v136, 7 bitop3:0x6c
	v_lshlrev_b32_e32 v151, 4, v1
	v_add_u32_e32 v1, 2, v136
	v_bitop3_b32 v1, v1, v0, 7 bitop3:0x78
	v_lshlrev_b32_e32 v145, 4, v1
	v_add_u32_e32 v1, 4, v136
	v_bitop3_b32 v1, v1, v0, 7 bitop3:0x78
	v_lshl_add_u32 v140, v136, 4, s0
	v_lshlrev_b32_e32 v146, 4, v1
	v_add_u32_e32 v1, 6, v136
	s_lshl_b32 s0, s37, 6
	v_bitop3_b32 v0, v1, v0, 7 bitop3:0x78
	s_sub_i32 s55, s0, 64
	s_or_b32 s0, s58, s60
	v_readlane_b32 s1, v255, 22
	v_lshlrev_b32_e32 v147, 4, v0
	v_add3_u32 v0, s66, v5, v142
	s_add_u32 s62, s1, s0
	v_readlane_b32 s1, v255, 23
	v_ashrrev_i32_e32 v1, 31, v0
	s_addc_u32 s63, s1, s59
	v_lshl_add_u64 v[118:119], v[0:1], 1, s[62:63]
	v_lshlrev_b32_e32 v0, 8, v4
	v_readlane_b32 s1, v255, 26
	s_waitcnt lgkmcnt(0)
	s_mov_b32 s41, 0
	s_mov_b32 s54, 2
	v_add3_u32 v0, s1, v0, v6
	v_readlane_b32 s1, v255, 24
	s_add_u32 s58, s1, s0
	v_readlane_b32 s0, v255, 25
	v_ashrrev_i32_e32 v1, 31, v0
	s_addc_u32 s59, s0, s59
	s_add_i32 s0, s51, s33
	v_lshl_add_u64 v[120:121], v[0:1], 1, s[58:59]
	v_add_u32_e32 v0, s0, v114
	v_sub_u32_e32 v152, v0, v141
	v_mov_b32_e32 v0, 0
	v_lshlrev_b32_e32 v144, 7, v114
	s_xor_b32 s64, s33, 0xffffff01
	s_mov_b32 s60, 0
	s_mov_b32 s65, 0
	v_mov_b32_e32 v1, v0
	v_mov_b32_e32 v2, v0
	v_mov_b32_e32 v3, v0
	v_mov_b32_e32 v4, v0
	v_mov_b32_e32 v5, v0
	v_mov_b32_e32 v6, v0
	v_mov_b32_e32 v7, v0
	v_mov_b32_e32 v8, v0
	v_mov_b32_e32 v9, v0
	v_mov_b32_e32 v10, v0
	v_mov_b32_e32 v11, v0
	v_mov_b32_e32 v12, v0
	v_mov_b32_e32 v13, v0
	v_mov_b32_e32 v14, v0
	v_mov_b32_e32 v15, v0
	v_mov_b32_e32 v16, v0
	v_mov_b32_e32 v17, v0
	v_mov_b32_e32 v18, v0
	v_mov_b32_e32 v19, v0
	v_mov_b32_e32 v20, v0
	v_mov_b32_e32 v21, v0
	v_mov_b32_e32 v22, v0
	v_mov_b32_e32 v23, v0
	v_mov_b32_e32 v24, v0
	v_mov_b32_e32 v25, v0
	v_mov_b32_e32 v26, v0
	v_mov_b32_e32 v27, v0
	v_mov_b32_e32 v28, v0
	v_mov_b32_e32 v29, v0
	v_mov_b32_e32 v30, v0
	v_mov_b32_e32 v31, v0
	s_branch .LBB0_232
